# static s_setprio 1 for waves 4..7 during the prompt NSA / retention-output task loops (one wave per SIMD prioritised); on top of v36
# speedup vs baseline: 1.0016x; 1.0016x over previous
; __device__ __forceinline__ unsigned xb_add(unsigned* p, unsigned v) { return __hip_atomic_fetch_add(p, v, __ATOMIC_RELAXED, __HIP_MEMORY_SCOPE_AGENT); }
; __global__ void __launch_bounds__(NWAVES * 64, 2) hybrid_fwd(Args args) {
;     ...
; #pragma unroll 1
;         for (;;) {
;             if (C.tid == 0) MISC[16] = xb_add(ctl + 320, 1u);
;             __syncthreads();
;             const unsigned qi = MISC[16];
;             __syncthreads();
;             if (qi >= 512u) break;
;             const int qbn = 255 - (int)(qi >> 1);
;             nsa_block_task(C, (qi & 1u) ? 511 - qbn : qbn, WSP(bf16, WS_ONSA));
;         }
.LBB0_1109:
	s_cmp_lt_u32 s33, 4
	s_cbranch_scc1 .Lnsa_prio0
	s_setprio 1

; #define LAS __attribute__((address_space(3)))
; __device__ __forceinline__ void ret_out_block(Ctx& C, int bt) {
;     const int lane = C.lane, r = lane & 15, fq = lane >> 4, w = C.wave;
;     const int h = bt & 3, c = bt >> 2, i0 = 128 * c + 16 * w;
;     LAS unsigned char* SP = C.lds;
;     LAS unsigned char* KI = C.lds + 65536;
;     const int l4 = launder_v(lane), rsub = l4 >> 4, pc = l4 & 15;
;     { const char* sp = (const char*)(WSP(bf16, WS_SPREV) + (size_t)(c * 4 + h) * 256 * 128);
; #pragma unroll
;       for (int i = 0; i < 8; ++i) { const int q = w + 8 * i, row = 4 * q + rsub;
;           __builtin_amdgcn_global_load_lds((const unsigned*)(sp + row * 256 + 16 * (pc ^ (row & 15))), (LAS unsigned*)(SP + q * 1024), 16, 0, 0); }
;       const char* kp = (const char*)(WSP(bf16, WS_RKI) + ((size_t)(128 * c) * 4 + h) * 128);
; #pragma unroll
;       for (int i = 0; i < 4; ++i) { const int q = w + 8 * i, row = 4 * q + rsub, f = (row & 3) | (((row >> 3) & 3) << 2);
;           __builtin_amdgcn_global_load_lds((const unsigned*)(kp + (size_t)row * 1024 + 16 * (pc ^ f)), (LAS unsigned*)(KI + q * 1024), 16, 0, 0); } }
;     bf16x8 bq[4];
;     { const bf16* qp = WSP(bf16, WS_RQD) + ((size_t)(i0 + r) * 4 + h) * 128 + 8 * fq;
; #pragma unroll
;       for (int s = 0; s < 4; ++s) bq[s] = *(const bf16x8*)(qp + 32 * s); }
;     const size_t ro = (size_t)(i0 + r) * 1024 + h * 256 + 4 * fq;
;     v2u sg[16];
; #pragma unroll
;     for (int et = 0; et < 16; ++et) sg[et] = *(const v2u*)(WSP(bf16, WS_SRG) + ro + 16 * et);
;     asm volatile("s_waitcnt vmcnt(0)" ::: "memory");
;     __syncthreads();
;     f4 o[16];
; #pragma unroll
;     for (int et = 0; et < 16; ++et) { o[et] = (f4){0.f, 0.f, 0.f, 0.f};
; #pragma unroll
;         for (int s = 0; s < 4; ++s) { const bf16x8 a = *(const LAS bf16x8*)(SP + (16 * et + r) * 256 + 16 * ((4 * s + fq) ^ r)); o[et] = MFMA16(a, bq[s], o[et]); } }
;     const int njc = (w >> 1) + 1;
;     bf16x8 pb[4];
; #pragma unroll
;     for (int jc = 0; jc < 4; ++jc) {
;         f4 s0 = (f4){0.f, 0.f, 0.f, 0.f}, s1 = s0;
;         if (jc < njc) {
; #pragma unroll
;             for (int kt = 0; kt < 2; ++kt) { const int kk = 32 * jc + 8 * (r >> 2) + 4 * kt + (r & 3);
; #pragma unroll
;                 for (int s = 0; s < 4; ++s) { const bf16x8 kf = *(const LAS bf16x8*)(KI + kk * 256 + 16 * ((4 * s + fq) ^ r));
.LBB0_1276:
	s_setprio 0
	s_or_b64 exec, exec, s[6:7]
	s_lshl_b32 s1, s33, 4
	s_waitcnt lgkmcnt(0)
	s_add_u32 s3, s90, 0x1758d900
	s_addc_u32 s79, s91, 0
	s_add_i32 s6, s33, 8
	s_lshl_b32 s85, s6, 2
	s_lshl_b32 s22, s6, 10
	s_add_i32 s6, s33, 16
	s_lshl_b32 s23, s6, 2
	s_lshl_b32 s24, s6, 10
	s_add_i32 s6, s33, 24
	s_lshl_b32 s25, s6, 2
	s_lshl_b32 s26, s6, 10
	s_add_i32 s6, s33, 32
	s_lshl_b32 s27, s6, 2
	s_lshl_b32 s40, s6, 10
	s_add_i32 s6, s33, 40
	s_lshl_b32 s28, s6, 2
	s_lshl_b32 s41, s6, 10
	s_add_i32 s6, s33, 48
	v_ashrrev_i32_e32 v0, 4, v160
	s_lshl_b32 s29, s6, 2
	s_lshl_b32 s42, s6, 10
	s_add_i32 s6, s33, 56
	v_bitop3_b32 v1, v0, v160, 15 bitop3:0x78
	s_lshl_b32 s0, s33, 2
	s_lshl_b32 s84, s33, 10
	s_lshl_b32 s30, s6, 2
	s_lshl_b32 s43, s6, 10
	v_lshlrev_b32_e32 v162, 4, v1
	v_add_u32_e32 v1, 4, v0
	s_add_u32 s31, s90, 0x828d900
	v_bitop3_b32 v1, v1, v160, 15 bitop3:0x78
	s_addc_u32 s34, s91, 0
	v_lshlrev_b32_e32 v116, 3, v0
	v_lshlrev_b32_e32 v118, 2, v0
	v_lshlrev_b32_e32 v163, 4, v1
	v_add_u32_e32 v1, 8, v0
	v_add_u32_e32 v0, 12, v0
	s_add_u32 s92, s90, 0x724d900
	v_bitop3_b32 v1, v1, v160, 15 bitop3:0x78
	v_bitop3_b32 v0, v0, v160, 15 bitop3:0x78
	s_addc_u32 s93, s91, 0
	v_lshlrev_b32_e32 v164, 4, v1
	v_lshlrev_b32_e32 v165, 4, v0
	v_lshlrev_b32_e32 v0, 1, v160
	v_and_b32_e32 v1, 3, v160
	v_and_b32_e32 v161, 15, v160
	s_add_u32 s94, s90, 0xc38d900
	v_and_or_b32 v0, v0, 24, v1
	s_addc_u32 s95, s91, 0
	v_or_b32_e32 v3, s1, v161
	v_lshlrev_b32_e32 v0, 8, v0
	s_add_i32 s6, 0, 0x10400
	v_or_b32_e32 v1, 4, v116
	v_add_u32_e32 v5, s6, v0
	v_cmp_gt_i32_e64 s[6:7], v1, v3
	v_or_b32_e32 v1, 5, v116
	v_cmp_gt_i32_e64 s[8:9], v1, v3
	v_or_b32_e32 v1, 6, v116
	v_cmp_gt_i32_e64 s[10:11], v1, v3
	v_or_b32_e32 v1, 7, v116
	v_cmp_gt_i32_e64 s[12:13], v1, v3
	v_or_b32_e32 v1, 2, v116
	v_cmp_gt_i32_e64 s[18:19], v1, v3
	v_or_b32_e32 v1, 3, v116
	v_cmp_gt_i32_e64 s[20:21], v1, v3
	v_add_u32_e32 v1, 32, v116
	v_cmp_gt_i32_e64 s[38:39], v1, v3
	v_readlane_b32 s37, v255, 12
	v_add_u32_e32 v1, 36, v116
	v_writelane_b32 v255, s38, 13
	s_add_i32 s35, 0, 0x10000
	s_cmpk_gt_u32 s37, 0x7f
	v_writelane_b32 v255, s39, 14
	v_cmp_gt_i32_e64 s[38:39], v1, v3
	v_add_u32_e32 v1, 33, v116
	s_cselect_b64 s[86:87], -1, 0
	v_writelane_b32 v255, s38, 21
	s_add_i32 s36, 0, 0x12000
	v_add_u32_e32 v166, s36, v0
	v_writelane_b32 v255, s39, 22
	v_cmp_gt_i32_e64 s[38:39], v1, v3
	v_add_u32_e32 v1, 37, v116
	s_add_i32 s36, 0, 0x12400
	v_writelane_b32 v255, s38, 23
	s_cmpk_gt_u32 s37, 0xff
	v_add_u32_e32 v167, s36, v0
	v_writelane_b32 v255, s39, 24
	v_cmp_gt_i32_e64 s[38:39], v1, v3
	v_add_u32_e32 v1, 34, v116
	s_cselect_b64 s[82:83], -1, 0
	v_writelane_b32 v255, s38, 19
	s_add_i32 s36, 0, 0x14000
	v_add_u32_e32 v168, s36, v0
	v_writelane_b32 v255, s39, 20
	v_cmp_gt_i32_e64 s[38:39], v1, v3
	v_add_u32_e32 v1, 38, v116
	s_add_i32 s36, 0, 0x14400
	v_writelane_b32 v255, s38, 25
	s_cmpk_gt_u32 s37, 0x17f
	v_add_u32_e32 v169, s36, v0
	v_writelane_b32 v255, s39, 26
	v_cmp_gt_i32_e64 s[38:39], v1, v3
	v_add_u32_e32 v1, 35, v116
	s_cselect_b64 s[88:89], -1, 0
	v_writelane_b32 v255, s38, 27
	s_add_i32 s36, 0, 0x16000
	v_add_u32_e32 v170, s36, v0
	v_writelane_b32 v255, s39, 28
	v_cmp_gt_i32_e64 s[38:39], v1, v3
	v_add_u32_e32 v1, 39, v116
	s_add_i32 s36, 0, 0x16400
	v_writelane_b32 v255, s38, 29
	v_add_u32_e32 v171, s36, v0
	s_add_u32 s36, s90, 0xa30d900
	v_writelane_b32 v255, s39, 30
	v_cmp_gt_i32_e64 s[38:39], v1, v3
	v_add_u32_e32 v1, 64, v116
	s_addc_u32 s37, s91, 0
	v_writelane_b32 v255, s38, 31
	v_ashrrev_i32_e32 v119, 31, v118
	v_add_u32_e32 v4, s35, v0
	v_writelane_b32 v255, s39, 32
	v_cmp_gt_i32_e64 s[38:39], v1, v3
	v_add_u32_e32 v1, 0x44, v116
	v_add_u32_e32 v0, 0x60, v116
	v_writelane_b32 v255, s38, 33
	s_add_u32 s80, s90, 0x1a5cd900
	v_lshl_add_u32 v2, v161, 8, 0
	v_writelane_b32 v255, s39, 34
	v_cmp_gt_i32_e64 s[38:39], v1, v3
	v_add_u32_e32 v1, 0x41, v116
	v_cmp_gt_i32_e64 s[56:57], v0, v3
	v_writelane_b32 v255, s38, 35
	v_add_u32_e32 v6, 0x64, v116
	v_add_u32_e32 v7, 0x61, v116
	v_writelane_b32 v255, s39, 36
	v_cmp_gt_i32_e64 s[38:39], v1, v3
	v_add_u32_e32 v1, 0x45, v116
	v_add_u32_e32 v8, 0x65, v116
	v_writelane_b32 v255, s38, 37
	v_add_u32_e32 v9, 0x62, v116
	v_add_u32_e32 v10, 0x66, v116
	v_writelane_b32 v255, s39, 38
	v_cmp_gt_i32_e64 s[38:39], v1, v3
	v_add_u32_e32 v1, 0x42, v116
	v_add_u32_e32 v11, 0x63, v116
	v_writelane_b32 v255, s38, 39
	v_add_u32_e32 v12, 0x67, v116
	s_addc_u32 s81, s91, 0
	v_writelane_b32 v255, s39, 40
	v_cmp_gt_i32_e64 s[38:39], v1, v3
	v_add_u32_e32 v1, 0x46, v116
	v_cmp_gt_i32_e64 s[50:51], v1, v3
	v_add_u32_e32 v1, 0x43, v116
	v_writelane_b32 v255, s38, 41
	v_cmp_gt_i32_e64 s[52:53], v1, v3
	v_add_u32_e32 v1, 0x47, v116
	v_writelane_b32 v255, s39, 42
	v_cmp_gt_i32_e64 s[54:55], v1, v3
	v_lshlrev_b64 v[0:1], 2, v[118:119]
	s_add_i32 s38, 0, 0x23040
	v_ashrrev_i32_e32 v117, 31, v116
	s_mov_b32 s97, 0
	v_cmp_gt_i32_e64 s[14:15], v116, v3
	v_cmp_lt_i32_e64 s[16:17], v116, v3
	v_lshl_add_u64 v[120:121], s[60:61], 0, v[0:1]
	v_lshl_add_u64 v[122:123], s[62:63], 0, v[0:1]
	v_mov_b32_e32 v172, 1
	v_mov_b32_e32 v125, 0
	v_add_u32_e32 v173, v2, v162
	v_add_u32_e32 v174, v2, v163
	v_add_u32_e32 v175, v2, v164
	v_add_u32_e32 v176, v2, v165
	v_add_u32_e32 v177, v4, v162
	v_add_u32_e32 v178, v4, v163
	v_add_u32_e32 v179, v4, v164
	v_add_u32_e32 v180, v4, v165
	v_add_u32_e32 v181, v5, v162
	v_add_u32_e32 v182, v5, v163
	v_add_u32_e32 v183, v5, v164
	v_add_u32_e32 v184, v5, v165
	v_cndmask_b32_e64 v185, 0, 1, s[86:87]
	s_mov_b32 s39, 0x8200
	v_mov_b32_e32 v186, 0x3727c5ac
	v_mov_b32_e32 v187, 0x260
	v_mov_b32_e32 v188, s38
	s_add_i32 s40, s40, 0
	s_add_i32 s41, s41, 0
	s_add_i32 s42, s42, 0
	s_add_i32 s43, s43, 0
	v_cmp_gt_i32_e64 s[58:59], v6, v3
	v_cmp_gt_i32_e64 s[60:61], v7, v3
	v_cmp_gt_i32_e64 s[62:63], v8, v3
	v_cmp_gt_i32_e64 s[64:65], v9, v3
	v_cmp_gt_i32_e64 s[66:67], v10, v3
	v_cmp_gt_i32_e64 s[68:69], v11, v3
	v_cmp_gt_i32_e64 s[70:71], v12, v3
	s_barrier
	s_branch .LBB0_1279
